# GEMM tile headers (phases 1,5,7,8): removed the early vmcnt(0) that drained the previous tile's epilogue stores before the next tile's first LDS-DMA could issue
# speedup vs baseline: 1.0023x; 1.0023x over previous
.LBB0_59:
	s_and_b32 s2, s2, 7
	v_readlane_b32 s4, v251, 7
	s_or_b32 s11, s2, s4
	s_lshl_b32 s10, s16, 7
	s_mul_i32 s2, s11, 0x160000
	s_add_u32 s4, s18, s2
	v_readlane_b32 s72, v250, 53
	s_addc_u32 s5, s19, 0
	s_mul_i32 s2, s16, 0xb0000
	v_readlane_b32 s84, v249, 1
	v_mov_b32_e32 v56, v200
	s_add_u32 s6, s84, s2
	s_movk_i32 s2, 0xb00
	v_ashrrev_i32_e32 v57, 2, v56
	v_lshlrev_b32_e32 v0, 3, v56
	s_nop 0
	v_and_b32_e32 v188, 24, v0
	v_mad_i64_i32 v[0:1], s[8:9], v57, s2, 0
	v_lshlrev_b64 v[178:179], 1, v[0:1]
	v_add_u32_e32 v0, 64, v57
	v_mad_i64_i32 v[0:1], s[8:9], v0, s2, 0
	s_mul_hi_u32 s7, s10, 0x1600
	v_readlane_b32 s85, v249, 2
	v_lshlrev_b64 v[180:181], 1, v[0:1]
	v_add_u32_e32 v0, 0x80, v57
	s_addc_u32 s7, s85, s7
	v_lshlrev_b32_e32 v196, 1, v188
	v_mad_i64_i32 v[44:45], s[8:9], v0, s2, 0
	v_add_u32_e32 v0, 0xc0, v57
	v_lshl_add_u64 v[176:177], s[4:5], 0, v[196:197]
	v_mad_i64_i32 v[48:49], s[8:9], v0, s2, 0
	v_lshl_add_u64 v[182:183], s[6:7], 0, v[196:197]
	v_lshl_add_u64 v[40:41], v[176:177], 0, v[178:179]
	v_lshl_add_u64 v[42:43], v[176:177], 0, v[180:181]
	v_lshl_add_u64 v[46:47], v[44:45], 1, v[176:177]
	v_lshl_add_u64 v[50:51], v[48:49], 1, v[176:177]
	v_lshl_add_u64 v[52:53], v[182:183], 0, v[178:179]
	v_lshl_add_u64 v[54:55], v[182:183], 0, v[180:181]
	v_and_b32_e32 v192, 63, v200
	v_readfirstlane_b32 s44, v200
	v_lshrrev_b32_e32 v193, 2, v192
	v_and_b32_e32 v194, 3, v192
	v_lshrrev_b32_e32 v201, 4, v192
	s_lshr_b32 s44, s44, 6
	v_xor_b32_e32 v206, v194, v201
	v_lshlrev_b32_e32 v206, 4, v206
	s_lshl_b32 s32, s44, 6
	v_add_u32_e32 v212, s32, v193
	v_mul_u32_u24_e32 v212, 0x1600, v212
	v_add_u32_e32 v234, v212, v206
	v_add_u32_e32 v235, 0x16000, v234
	v_add_u32_e32 v236, 0x2c000, v234
	v_add_u32_e32 v237, 0x42000, v234
	s_lshl_b32 s32, s44, 5
	v_add_u32_e32 v212, s32, v193
	v_mul_u32_u24_e32 v212, 0x1600, v212
	v_add_u32_e32 v238, v212, v206
	v_add_u32_e32 v239, 0x16000, v238
	v_and_b32_e32 v193, 31, v192
	v_lshrrev_b32_e32 v194, 5, v192
	v_bfe_u32 v201, v192, 2, 2
	v_xor_b32_e32 v206, v194, v201
	v_lshlrev_b32_e32 v206, 4, v206
	v_lshl_add_u32 v206, v193, 6, v206
	s_lshr_b32 s32, s44, 1
	s_lshl_b32 s32, s32, 13
	v_add_u32_e32 v240, s32, v206
	v_xor_b32_e32 v241, 32, v240
	s_and_b32 s32, s44, 1
	s_lshl_b32 s32, s32, 12
	s_add_u32 s32, s32, 0x4000
	v_add_u32_e32 v242, s32, v206
	v_xor_b32_e32 v243, 32, v242
	s_lshl_b32 s46, s44, 12
	s_lshl_b32 s47, s44, 11
	s_add_u32 s47, s47, 0x4000
	s_mov_b32 s40, s4
	s_mov_b32 s41, s5
	s_mov_b32 s42, s6
	s_mov_b32 s43, s7
	s_add_u32 m0, s46, 0x0
	s_nop 0
	global_load_lds_dwordx4 v234, s[40:41]
	s_add_u32 m0, m0, 0x400
	s_nop 0
	global_load_lds_dwordx4 v235, s[40:41]
	s_add_u32 m0, m0, 0x400
	s_nop 0
	global_load_lds_dwordx4 v236, s[40:41]
	s_add_u32 m0, m0, 0x400
	s_nop 0
	global_load_lds_dwordx4 v237, s[40:41]
	s_add_u32 m0, s47, 0x0
	s_nop 0
	global_load_lds_dwordx4 v238, s[42:43]
	s_add_u32 m0, m0, 0x400
	s_nop 0
	global_load_lds_dwordx4 v239, s[42:43]
	s_add_u32 s40, s40, 64
	s_addc_u32 s41, s41, 0
	s_add_u32 s42, s42, 64
	s_addc_u32 s43, s43, 0
	s_add_u32 m0, s46, 0x6000
	s_nop 0
	global_load_lds_dwordx4 v234, s[40:41]
	s_add_u32 m0, m0, 0x400
	s_nop 0
	global_load_lds_dwordx4 v235, s[40:41]
	s_add_u32 m0, m0, 0x400
	s_nop 0
	global_load_lds_dwordx4 v236, s[40:41]
	s_add_u32 m0, m0, 0x400
	s_nop 0
	global_load_lds_dwordx4 v237, s[40:41]
	s_add_u32 m0, s47, 0x6000
	s_nop 0
	global_load_lds_dwordx4 v238, s[42:43]
	s_add_u32 m0, m0, 0x400
	s_nop 0
	global_load_lds_dwordx4 v239, s[42:43]
	s_add_u32 s40, s40, 64
	s_addc_u32 s41, s41, 0
	s_add_u32 s42, s42, 64
	s_addc_u32 s43, s43, 0
	s_mov_b32 s45, 0xc000
	s_mov_b32 s49, 0
	v_and_b32_e32 v58, 0xfffff9f, v56
	v_lshrrev_b32_e32 v59, 1, v56
	v_and_b32_e32 v56, 0x5f, v56
	s_movk_i32 s2, 0x50
	v_and_b32_e32 v59, 16, v59
	v_mad_u32_u24 v56, v56, s2, 0
	v_mul_lo_u32 v57, v57, s2
	v_mul_lo_u32 v58, v58, s2
	v_add_u32_e32 v189, v56, v59
	v_add_u32_e32 v56, 0, v196
	v_mov_b32_e32 v0, 0
	v_add_u32_e32 v58, 0, v58
	v_add_u32_e32 v191, v56, v57
	s_mov_b32 s17, 64
	s_mov_b32 s18, 0
	v_mov_b32_e32 v1, v0
	v_mov_b32_e32 v2, v0
	v_mov_b32_e32 v3, v0
	v_mov_b32_e32 v4, v0
	v_mov_b32_e32 v5, v0
	v_mov_b32_e32 v6, v0
	v_mov_b32_e32 v7, v0
	v_mov_b32_e32 v8, v0
	v_mov_b32_e32 v9, v0
	v_mov_b32_e32 v10, v0
	v_mov_b32_e32 v11, v0
	v_mov_b32_e32 v12, v0
	v_mov_b32_e32 v13, v0
	v_mov_b32_e32 v14, v0
	v_mov_b32_e32 v15, v0
	v_lshlrev_b64 v[184:185], 1, v[44:45]
	v_lshlrev_b64 v[186:187], 1, v[48:49]
	v_add_u32_e32 v190, v58, v59
	v_mov_b32_e32 v40, v0
	v_mov_b32_e32 v41, v0
	v_mov_b32_e32 v42, v0
	v_mov_b32_e32 v43, v0
	v_mov_b32_e32 v44, v0
	v_mov_b32_e32 v45, v0
	v_mov_b32_e32 v46, v0
	v_mov_b32_e32 v47, v0
	v_mov_b32_e32 v16, v0
	v_mov_b32_e32 v17, v0
	v_mov_b32_e32 v18, v0
	v_mov_b32_e32 v19, v0
	v_mov_b32_e32 v20, v0
	v_mov_b32_e32 v21, v0
	v_mov_b32_e32 v22, v0
	v_mov_b32_e32 v23, v0
	v_mov_b32_e32 v24, v0
	v_mov_b32_e32 v25, v0
	v_mov_b32_e32 v26, v0
	v_mov_b32_e32 v27, v0
	v_mov_b32_e32 v28, v0
	v_mov_b32_e32 v29, v0
	v_mov_b32_e32 v30, v0
	v_mov_b32_e32 v31, v0
	v_mov_b32_e32 v32, v0
	v_mov_b32_e32 v33, v0
	v_mov_b32_e32 v34, v0
	v_mov_b32_e32 v35, v0
	v_mov_b32_e32 v36, v0
	v_mov_b32_e32 v37, v0
	v_mov_b32_e32 v38, v0
	v_mov_b32_e32 v39, v0
	v_mov_b32_e32 v48, v0
	v_mov_b32_e32 v49, v0
	v_mov_b32_e32 v50, v0
	v_mov_b32_e32 v51, v0
	v_mov_b32_e32 v52, v0
	v_mov_b32_e32 v53, v0
	v_mov_b32_e32 v54, v0
	v_mov_b32_e32 v55, v0
	v_mov_b32_e32 v56, v0
	v_mov_b32_e32 v57, v0
	v_mov_b32_e32 v58, v0
	v_mov_b32_e32 v59, v0
	v_mov_b32_e32 v60, v0
	v_mov_b32_e32 v61, v0
	v_mov_b32_e32 v62, v0
	v_mov_b32_e32 v63, v0
	v_mov_b32_e32 v64, v0
	v_mov_b32_e32 v65, v0
	v_mov_b32_e32 v66, v0
	v_mov_b32_e32 v67, v0
	v_mov_b32_e32 v68, v0
	v_mov_b32_e32 v69, v0
	v_mov_b32_e32 v70, v0
	v_mov_b32_e32 v71, v0
	v_mov_b32_e32 v72, v0
	v_mov_b32_e32 v73, v0
	v_mov_b32_e32 v74, v0
	v_mov_b32_e32 v75, v0
	v_mov_b32_e32 v76, v0
	v_mov_b32_e32 v77, v0
	v_mov_b32_e32 v78, v0
	v_mov_b32_e32 v79, v0
	v_mov_b32_e32 v80, v0
	v_mov_b32_e32 v81, v0
	v_mov_b32_e32 v82, v0
	v_mov_b32_e32 v83, v0
	v_mov_b32_e32 v84, v0
	v_mov_b32_e32 v85, v0
	v_mov_b32_e32 v86, v0
	v_mov_b32_e32 v87, v0
	v_mov_b32_e32 v88, v0
	v_mov_b32_e32 v89, v0
	v_mov_b32_e32 v90, v0
	v_mov_b32_e32 v91, v0
	v_mov_b32_e32 v92, v0
	v_mov_b32_e32 v93, v0
	v_mov_b32_e32 v94, v0
	v_mov_b32_e32 v95, v0
	v_mov_b32_e32 v96, v0
	v_mov_b32_e32 v97, v0
	v_mov_b32_e32 v98, v0
	v_mov_b32_e32 v99, v0
	v_mov_b32_e32 v100, v0
	v_mov_b32_e32 v101, v0
	v_mov_b32_e32 v102, v0
	v_mov_b32_e32 v103, v0
	v_mov_b32_e32 v104, v0
	v_mov_b32_e32 v105, v0
	v_mov_b32_e32 v106, v0
	v_mov_b32_e32 v107, v0
	v_mov_b32_e32 v108, v0
	v_mov_b32_e32 v109, v0
	v_mov_b32_e32 v110, v0
	v_mov_b32_e32 v111, v0
	v_mov_b32_e32 v112, v0
	v_mov_b32_e32 v113, v0
	v_mov_b32_e32 v114, v0
	v_mov_b32_e32 v115, v0
	v_mov_b32_e32 v116, v0
	v_mov_b32_e32 v117, v0
	v_mov_b32_e32 v118, v0
	v_mov_b32_e32 v119, v0
	v_mov_b32_e32 v120, v0
	v_mov_b32_e32 v121, v0
	v_mov_b32_e32 v122, v0
	v_mov_b32_e32 v123, v0
	v_mov_b32_e32 v124, v0
	v_mov_b32_e32 v125, v0
	v_mov_b32_e32 v126, v0
	v_mov_b32_e32 v127, v0
	v_readlane_b32 s73, v250, 54
	v_readlane_b32 s74, v250, 55
	v_readlane_b32 s75, v250, 56
	v_readlane_b32 s76, v250, 57
	v_readlane_b32 s77, v250, 58
	v_readlane_b32 s78, v250, 59
	v_readlane_b32 s79, v250, 60
	v_readlane_b32 s80, v250, 61
	v_readlane_b32 s81, v250, 62
	v_readlane_b32 s82, v250, 63
	v_readlane_b32 s83, v249, 0
	v_readlane_b32 s86, v249, 3
	v_readlane_b32 s87, v249, 4
	s_waitcnt vmcnt(6)
	s_waitcnt lgkmcnt(0)
	v_readlane_b32 s44, v251, 5
	s_nop 0
	s_bitcmp1_b32 s44, 5
	s_cbranch_scc0 .Lnoprio_1
	s_setprio 2

.LBB0_75:
	s_and_b32 s4, s2, 7
	v_readlane_b32 s5, v251, 7
	s_or_b32 s11, s4, s5
	v_readlane_b32 s16, v250, 53
	s_lshr_b32 s10, s2, 3
	s_lshl_b32 s2, s11, 19
	v_readlane_b32 s22, v250, 59
	v_mov_b32_e32 v13, v200
	v_readlane_b32 s23, v250, 60
	s_add_u32 s4, s22, s2
	v_readlane_b32 s26, v250, 63
	v_ashrrev_i32_e32 v38, 2, v13
	v_lshlrev_b32_e32 v0, 3, v13
	s_addc_u32 s5, s23, 0
	s_lshl_b32 s2, s10, 18
	s_nop 0
	v_and_b32_e32 v188, 24, v0
	v_add_u32_e32 v46, 0x80, v38
	v_readlane_b32 s27, v249, 0
	s_add_u32 s6, s26, s2
	v_lshlrev_b32_e32 v196, 1, v188
	v_add_u32_e32 v42, 64, v38
	v_ashrrev_i32_e32 v47, 31, v46
	v_add_u32_e32 v50, 0xc0, v38
	s_addc_u32 s7, s27, 0
	v_lshl_add_u64 v[176:177], s[4:5], 0, v[196:197]
	v_ashrrev_i32_e32 v39, 31, v38
	v_ashrrev_i32_e32 v43, 31, v42
	v_lshlrev_b64 v[4:5], 11, v[46:47]
	v_ashrrev_i32_e32 v51, 31, v50
	v_lshlrev_b64 v[0:1], 11, v[38:39]
	v_lshlrev_b64 v[2:3], 11, v[42:43]
	v_lshl_add_u64 v[48:49], v[176:177], 0, v[4:5]
	v_lshlrev_b64 v[4:5], 11, v[50:51]
	v_lshl_add_u64 v[178:179], s[6:7], 0, v[196:197]
	v_lshl_add_u64 v[40:41], v[176:177], 0, v[0:1]
	v_lshl_add_u64 v[44:45], v[176:177], 0, v[2:3]
	v_lshl_add_u64 v[52:53], v[176:177], 0, v[4:5]
	v_lshl_add_u64 v[54:55], v[178:179], 0, v[0:1]
	v_lshl_add_u64 v[56:57], v[178:179], 0, v[2:3]
	v_and_b32_e32 v192, 63, v200
	v_readfirstlane_b32 s44, v200
	v_lshrrev_b32_e32 v193, 2, v192
	v_and_b32_e32 v194, 3, v192
	v_lshrrev_b32_e32 v201, 4, v192
	s_lshr_b32 s44, s44, 6
	v_xor_b32_e32 v206, v194, v201
	v_lshlrev_b32_e32 v206, 4, v206
	s_lshl_b32 s32, s44, 6
	v_add_u32_e32 v212, s32, v193
	v_lshlrev_b32_e32 v212, 11, v212
	v_add_u32_e32 v234, v212, v206
	v_add_u32_e32 v235, 0x8000, v234
	v_add_u32_e32 v236, 0x10000, v234
	v_add_u32_e32 v237, 0x18000, v234
	s_lshl_b32 s32, s44, 5
	v_add_u32_e32 v212, s32, v193
	v_lshlrev_b32_e32 v212, 11, v212
	v_add_u32_e32 v238, v212, v206
	v_add_u32_e32 v239, 0x8000, v238
	v_and_b32_e32 v193, 31, v192
	v_lshrrev_b32_e32 v194, 5, v192
	v_bfe_u32 v201, v192, 2, 2
	v_xor_b32_e32 v206, v194, v201
	v_lshlrev_b32_e32 v206, 4, v206
	v_lshl_add_u32 v206, v193, 6, v206
	s_lshr_b32 s32, s44, 1
	s_lshl_b32 s32, s32, 13
	v_add_u32_e32 v240, s32, v206
	v_xor_b32_e32 v241, 32, v240
	s_and_b32 s32, s44, 1
	s_lshl_b32 s32, s32, 12
	s_add_u32 s32, s32, 0x4000
	v_add_u32_e32 v242, s32, v206
	v_xor_b32_e32 v243, 32, v242
	s_lshl_b32 s46, s44, 12
	s_lshl_b32 s47, s44, 11
	s_add_u32 s47, s47, 0x4000
	s_mov_b32 s40, s4
	s_mov_b32 s41, s5
	s_mov_b32 s42, s6
	s_mov_b32 s43, s7
	s_add_u32 m0, s46, 0x0
	s_nop 0
	global_load_lds_dwordx4 v234, s[40:41]
	s_add_u32 m0, m0, 0x400
	s_nop 0
	global_load_lds_dwordx4 v235, s[40:41]
	s_add_u32 m0, m0, 0x400
	s_nop 0
	global_load_lds_dwordx4 v236, s[40:41]
	s_add_u32 m0, m0, 0x400
	s_nop 0
	global_load_lds_dwordx4 v237, s[40:41]
	s_add_u32 m0, s47, 0x0
	s_nop 0
	global_load_lds_dwordx4 v238, s[42:43]
	s_add_u32 m0, m0, 0x400
	s_nop 0
	global_load_lds_dwordx4 v239, s[42:43]
	s_add_u32 s40, s40, 64
	s_addc_u32 s41, s41, 0
	s_add_u32 s42, s42, 64
	s_addc_u32 s43, s43, 0
	s_add_u32 m0, s46, 0x6000
	s_nop 0
	global_load_lds_dwordx4 v234, s[40:41]
	s_add_u32 m0, m0, 0x400
	s_nop 0
	global_load_lds_dwordx4 v235, s[40:41]
	s_add_u32 m0, m0, 0x400
	s_nop 0
	global_load_lds_dwordx4 v236, s[40:41]
	s_add_u32 m0, m0, 0x400
	s_nop 0
	global_load_lds_dwordx4 v237, s[40:41]
	s_add_u32 m0, s47, 0x6000
	s_nop 0
	global_load_lds_dwordx4 v238, s[42:43]
	s_add_u32 m0, m0, 0x400
	s_nop 0
	global_load_lds_dwordx4 v239, s[42:43]
	s_add_u32 s40, s40, 64
	s_addc_u32 s41, s41, 0
	s_add_u32 s42, s42, 64
	s_addc_u32 s43, s43, 0
	s_mov_b32 s45, 0xc000
	s_mov_b32 s49, 0
	v_and_b32_e32 v58, 0xfffff9f, v13
	v_lshrrev_b32_e32 v59, 1, v13
	v_and_b32_e32 v13, 0x5f, v13
	s_movk_i32 s2, 0x50
	v_and_b32_e32 v59, 16, v59
	v_mad_u32_u24 v13, v13, s2, 0
	v_mul_lo_u32 v60, v38, s2
	v_mul_lo_u32 v58, v58, s2
	v_add_u32_e32 v189, v13, v59
	v_add_u32_e32 v13, 0, v196
	v_readlane_b32 s17, v250, 54
	v_mov_b32_e32 v0, 0
	v_lshlrev_b64 v[38:39], 10, v[38:39]
	v_add_u32_e32 v58, 0, v58
	v_lshlrev_b64 v[42:43], 10, v[42:43]
	v_lshlrev_b64 v[46:47], 10, v[46:47]
	v_lshlrev_b64 v[50:51], 10, v[50:51]
	v_add_u32_e32 v191, v13, v60
	s_mov_b32 s16, 64
	s_mov_b32 s17, 0
	v_mov_b32_e32 v1, v0
	v_mov_b32_e32 v2, v0
	v_mov_b32_e32 v3, v0
	v_mov_b32_e32 v4, v0
	v_mov_b32_e32 v5, v0
	v_mov_b32_e32 v6, v0
	v_mov_b32_e32 v7, v0
	v_mov_b32_e32 v8, v0
	v_mov_b32_e32 v9, v0
	v_mov_b32_e32 v10, v0
	v_mov_b32_e32 v11, v0
	v_mov_b32_e32 v12, v0
	v_lshlrev_b64 v[180:181], 1, v[38:39]
	v_add_u32_e32 v190, v58, v59
	v_lshlrev_b64 v[182:183], 1, v[42:43]
	v_lshlrev_b64 v[184:185], 1, v[46:47]
	v_lshlrev_b64 v[186:187], 1, v[50:51]
	v_mov_b32_e32 v13, v0
	v_mov_b32_e32 v38, v0
	v_mov_b32_e32 v39, v0
	v_mov_b32_e32 v14, v0
	v_mov_b32_e32 v15, v0
	v_mov_b32_e32 v16, v0
	v_mov_b32_e32 v17, v0
	v_mov_b32_e32 v18, v0
	v_mov_b32_e32 v19, v0
	v_mov_b32_e32 v20, v0
	v_mov_b32_e32 v21, v0
	v_mov_b32_e32 v22, v0
	v_mov_b32_e32 v23, v0
	v_mov_b32_e32 v24, v0
	v_mov_b32_e32 v25, v0
	v_mov_b32_e32 v26, v0
	v_mov_b32_e32 v27, v0
	v_mov_b32_e32 v28, v0
	v_mov_b32_e32 v29, v0
	v_mov_b32_e32 v30, v0
	v_mov_b32_e32 v31, v0
	v_mov_b32_e32 v32, v0
	v_mov_b32_e32 v33, v0
	v_mov_b32_e32 v34, v0
	v_mov_b32_e32 v35, v0
	v_mov_b32_e32 v36, v0
	v_mov_b32_e32 v37, v0
	v_mov_b32_e32 v40, v0
	v_mov_b32_e32 v41, v0
	v_mov_b32_e32 v42, v0
	v_mov_b32_e32 v43, v0
	v_mov_b32_e32 v44, v0
	v_mov_b32_e32 v45, v0
	v_mov_b32_e32 v46, v0
	v_mov_b32_e32 v47, v0
	v_mov_b32_e32 v48, v0
	v_mov_b32_e32 v49, v0
	v_mov_b32_e32 v50, v0
	v_mov_b32_e32 v51, v0
	v_mov_b32_e32 v52, v0
	v_mov_b32_e32 v53, v0
	v_mov_b32_e32 v54, v0
	v_mov_b32_e32 v55, v0
	v_mov_b32_e32 v56, v0
	v_mov_b32_e32 v57, v0
	v_mov_b32_e32 v58, v0
	v_mov_b32_e32 v59, v0
	v_mov_b32_e32 v60, v0
	v_mov_b32_e32 v61, v0
	v_mov_b32_e32 v62, v0
	v_mov_b32_e32 v63, v0
	v_mov_b32_e32 v64, v0
	v_mov_b32_e32 v65, v0
	v_mov_b32_e32 v66, v0
	v_mov_b32_e32 v67, v0
	v_mov_b32_e32 v68, v0
	v_mov_b32_e32 v69, v0
	v_mov_b32_e32 v70, v0
	v_mov_b32_e32 v71, v0
	v_mov_b32_e32 v72, v0
	v_mov_b32_e32 v73, v0
	v_mov_b32_e32 v74, v0
	v_mov_b32_e32 v75, v0
	v_mov_b32_e32 v76, v0
	v_mov_b32_e32 v77, v0
	v_mov_b32_e32 v78, v0
	v_mov_b32_e32 v79, v0
	v_mov_b32_e32 v80, v0
	v_mov_b32_e32 v81, v0
	v_mov_b32_e32 v82, v0
	v_mov_b32_e32 v83, v0
	v_mov_b32_e32 v84, v0
	v_mov_b32_e32 v85, v0
	v_mov_b32_e32 v86, v0
	v_mov_b32_e32 v87, v0
	v_mov_b32_e32 v88, v0
	v_mov_b32_e32 v89, v0
	v_mov_b32_e32 v90, v0
	v_mov_b32_e32 v91, v0
	v_mov_b32_e32 v92, v0
	v_mov_b32_e32 v93, v0
	v_mov_b32_e32 v94, v0
	v_mov_b32_e32 v95, v0
	v_mov_b32_e32 v96, v0
	v_mov_b32_e32 v97, v0
	v_mov_b32_e32 v98, v0
	v_mov_b32_e32 v99, v0
	v_mov_b32_e32 v100, v0
	v_mov_b32_e32 v101, v0
	v_mov_b32_e32 v102, v0
	v_mov_b32_e32 v103, v0
	v_mov_b32_e32 v104, v0
	v_mov_b32_e32 v105, v0
	v_mov_b32_e32 v106, v0
	v_mov_b32_e32 v107, v0
	v_mov_b32_e32 v108, v0
	v_mov_b32_e32 v109, v0
	v_mov_b32_e32 v110, v0
	v_mov_b32_e32 v111, v0
	v_mov_b32_e32 v112, v0
	v_mov_b32_e32 v113, v0
	v_mov_b32_e32 v114, v0
	v_mov_b32_e32 v115, v0
	v_mov_b32_e32 v116, v0
	v_mov_b32_e32 v117, v0
	v_mov_b32_e32 v118, v0
	v_mov_b32_e32 v119, v0
	v_mov_b32_e32 v120, v0
	v_mov_b32_e32 v121, v0
	v_mov_b32_e32 v122, v0
	v_mov_b32_e32 v123, v0
	v_mov_b32_e32 v124, v0
	v_mov_b32_e32 v125, v0
	v_mov_b32_e32 v126, v0
	v_mov_b32_e32 v127, v0
	v_readlane_b32 s18, v250, 55
	v_readlane_b32 s19, v250, 56
	v_readlane_b32 s20, v250, 57
	v_readlane_b32 s21, v250, 58
	v_readlane_b32 s24, v250, 61
	v_readlane_b32 s25, v250, 62
	v_readlane_b32 s28, v249, 1
	v_readlane_b32 s29, v249, 2
	v_readlane_b32 s30, v249, 3
	v_readlane_b32 s31, v249, 4
	s_waitcnt vmcnt(6)
	s_waitcnt lgkmcnt(0)
	v_readlane_b32 s44, v251, 5
	s_nop 0
	s_bitcmp1_b32 s44, 5
	s_cbranch_scc0 .Lnoprio_0
	s_setprio 2

.LBB0_106:
	s_and_b32 s2, s2, 7
	v_readlane_b32 s4, v251, 7
	s_or_b32 s16, s2, s4
	s_lshl_b32 s4, s15, 7
	s_lshl_b32 s14, s16, 19
	v_mov_b32_e32 v56, v200
	s_add_u32 s6, s20, s14
	s_mov_b32 s5, s3
	s_addc_u32 s7, s21, 0
	v_ashrrev_i32_e32 v36, 2, v56
	v_lshlrev_b32_e32 v0, 3, v56
	s_lshl_b64 s[8:9], s[4:5], 11
	v_readlane_b32 s10, v249, 19
	s_nop 0
	v_and_b32_e32 v188, 24, v0
	v_add_u32_e32 v44, 0x80, v36
	v_readlane_b32 s11, v249, 20
	s_add_u32 s8, s10, s8
	v_lshlrev_b32_e32 v196, 1, v188
	v_add_u32_e32 v40, 64, v36
	v_ashrrev_i32_e32 v45, 31, v44
	v_add_u32_e32 v48, 0xc0, v36
	s_addc_u32 s9, s11, s9
	v_lshl_add_u64 v[176:177], s[6:7], 0, v[196:197]
	v_ashrrev_i32_e32 v37, 31, v36
	v_ashrrev_i32_e32 v41, 31, v40
	v_lshlrev_b64 v[4:5], 11, v[44:45]
	v_ashrrev_i32_e32 v49, 31, v48
	v_lshlrev_b64 v[0:1], 11, v[36:37]
	v_lshlrev_b64 v[2:3], 11, v[40:41]
	v_lshl_add_u64 v[46:47], v[176:177], 0, v[4:5]
	v_lshlrev_b64 v[4:5], 11, v[48:49]
	v_lshl_add_u64 v[178:179], s[8:9], 0, v[196:197]
	v_lshl_add_u64 v[38:39], v[176:177], 0, v[0:1]
	v_lshl_add_u64 v[42:43], v[176:177], 0, v[2:3]
	v_lshl_add_u64 v[50:51], v[176:177], 0, v[4:5]
	v_lshl_add_u64 v[52:53], v[178:179], 0, v[0:1]
	v_lshl_add_u64 v[54:55], v[178:179], 0, v[2:3]
	v_and_b32_e32 v192, 63, v200
	v_readfirstlane_b32 s44, v200
	v_lshrrev_b32_e32 v193, 2, v192
	v_and_b32_e32 v194, 3, v192
	v_lshrrev_b32_e32 v201, 4, v192
	s_lshr_b32 s44, s44, 6
	v_xor_b32_e32 v206, v194, v201
	v_lshlrev_b32_e32 v206, 4, v206
	s_lshl_b32 s32, s44, 6
	v_add_u32_e32 v212, s32, v193
	v_lshlrev_b32_e32 v212, 11, v212
	v_add_u32_e32 v234, v212, v206
	v_add_u32_e32 v235, 0x8000, v234
	v_add_u32_e32 v236, 0x10000, v234
	v_add_u32_e32 v237, 0x18000, v234
	s_lshl_b32 s32, s44, 5
	v_add_u32_e32 v212, s32, v193
	v_lshlrev_b32_e32 v212, 11, v212
	v_add_u32_e32 v238, v212, v206
	v_add_u32_e32 v239, 0x8000, v238
	v_and_b32_e32 v193, 31, v192
	v_lshrrev_b32_e32 v194, 5, v192
	v_bfe_u32 v201, v192, 2, 2
	v_xor_b32_e32 v206, v194, v201
	v_lshlrev_b32_e32 v206, 4, v206
	v_lshl_add_u32 v206, v193, 6, v206
	s_lshr_b32 s32, s44, 1
	s_lshl_b32 s32, s32, 13
	v_add_u32_e32 v240, s32, v206
	v_xor_b32_e32 v241, 32, v240
	s_and_b32 s32, s44, 1
	s_lshl_b32 s32, s32, 12
	s_add_u32 s32, s32, 0x4000
	v_add_u32_e32 v242, s32, v206
	v_xor_b32_e32 v243, 32, v242
	s_lshl_b32 s46, s44, 12
	s_lshl_b32 s47, s44, 11
	s_add_u32 s47, s47, 0x4000
	s_mov_b32 s40, s6
	s_mov_b32 s41, s7
	s_mov_b32 s42, s8
	s_mov_b32 s43, s9
	s_add_u32 m0, s46, 0x0
	s_nop 0
	global_load_lds_dwordx4 v234, s[40:41]
	s_add_u32 m0, m0, 0x400
	s_nop 0
	global_load_lds_dwordx4 v235, s[40:41]
	s_add_u32 m0, m0, 0x400
	s_nop 0
	global_load_lds_dwordx4 v236, s[40:41]
	s_add_u32 m0, m0, 0x400
	s_nop 0
	global_load_lds_dwordx4 v237, s[40:41]
	s_add_u32 m0, s47, 0x0
	s_nop 0
	global_load_lds_dwordx4 v238, s[42:43]
	s_add_u32 m0, m0, 0x400
	s_nop 0
	global_load_lds_dwordx4 v239, s[42:43]
	s_add_u32 s40, s40, 64
	s_addc_u32 s41, s41, 0
	s_add_u32 s42, s42, 64
	s_addc_u32 s43, s43, 0
	s_add_u32 m0, s46, 0x6000
	s_nop 0
	global_load_lds_dwordx4 v234, s[40:41]
	s_add_u32 m0, m0, 0x400
	s_nop 0
	global_load_lds_dwordx4 v235, s[40:41]
	s_add_u32 m0, m0, 0x400
	s_nop 0
	global_load_lds_dwordx4 v236, s[40:41]
	s_add_u32 m0, m0, 0x400
	s_nop 0
	global_load_lds_dwordx4 v237, s[40:41]
	s_add_u32 m0, s47, 0x6000
	s_nop 0
	global_load_lds_dwordx4 v238, s[42:43]
	s_add_u32 m0, m0, 0x400
	s_nop 0
	global_load_lds_dwordx4 v239, s[42:43]
	s_add_u32 s40, s40, 64
	s_addc_u32 s41, s41, 0
	s_add_u32 s42, s42, 64
	s_addc_u32 s43, s43, 0
	s_mov_b32 s45, 0xc000
	s_mov_b32 s49, 0
	v_and_b32_e32 v57, 0xfffff9f, v56
	v_lshrrev_b32_e32 v58, 1, v56
	v_and_b32_e32 v56, 0x5f, v56
	s_movk_i32 s2, 0x50
	v_and_b32_e32 v58, 16, v58
	v_mad_u32_u24 v56, v56, s2, 0
	v_mul_lo_u32 v59, v36, s2
	v_mul_lo_u32 v57, v57, s2
	v_add_u32_e32 v189, v56, v58
	v_add_u32_e32 v56, 0, v196
	v_mov_b32_e32 v0, 0
	v_lshlrev_b64 v[36:37], 10, v[36:37]
	v_add_u32_e32 v57, 0, v57
	v_lshlrev_b64 v[40:41], 10, v[40:41]
	v_lshlrev_b64 v[44:45], 10, v[44:45]
	v_lshlrev_b64 v[48:49], 10, v[48:49]
	v_add_u32_e32 v191, v56, v59
	s_mov_b32 s5, 64
	s_mov_b32 s17, 0
	v_mov_b32_e32 v1, v0
	v_mov_b32_e32 v2, v0
	v_mov_b32_e32 v3, v0
	v_mov_b32_e32 v4, v0
	v_mov_b32_e32 v5, v0
	v_mov_b32_e32 v6, v0
	v_mov_b32_e32 v7, v0
	v_mov_b32_e32 v8, v0
	v_mov_b32_e32 v9, v0
	v_mov_b32_e32 v10, v0
	v_mov_b32_e32 v11, v0
	v_lshlrev_b64 v[180:181], 1, v[36:37]
	v_add_u32_e32 v190, v57, v58
	v_lshlrev_b64 v[182:183], 1, v[40:41]
	v_lshlrev_b64 v[184:185], 1, v[44:45]
	v_lshlrev_b64 v[186:187], 1, v[48:49]
	v_mov_b32_e32 v36, v0
	v_mov_b32_e32 v37, v0
	v_mov_b32_e32 v38, v0
	v_mov_b32_e32 v39, v0
	v_mov_b32_e32 v40, v0
	v_mov_b32_e32 v41, v0
	v_mov_b32_e32 v42, v0
	v_mov_b32_e32 v12, v0
	v_mov_b32_e32 v13, v0
	v_mov_b32_e32 v14, v0
	v_mov_b32_e32 v15, v0
	v_mov_b32_e32 v16, v0
	v_mov_b32_e32 v17, v0
	v_mov_b32_e32 v18, v0
	v_mov_b32_e32 v19, v0
	v_mov_b32_e32 v20, v0
	v_mov_b32_e32 v21, v0
	v_mov_b32_e32 v22, v0
	v_mov_b32_e32 v23, v0
	v_mov_b32_e32 v24, v0
	v_mov_b32_e32 v25, v0
	v_mov_b32_e32 v26, v0
	v_mov_b32_e32 v27, v0
	v_mov_b32_e32 v28, v0
	v_mov_b32_e32 v29, v0
	v_mov_b32_e32 v30, v0
	v_mov_b32_e32 v31, v0
	v_mov_b32_e32 v32, v0
	v_mov_b32_e32 v33, v0
	v_mov_b32_e32 v34, v0
	v_mov_b32_e32 v35, v0
	v_mov_b32_e32 v43, v0
	v_mov_b32_e32 v44, v0
	v_mov_b32_e32 v45, v0
	v_mov_b32_e32 v46, v0
	v_mov_b32_e32 v47, v0
	v_mov_b32_e32 v48, v0
	v_mov_b32_e32 v49, v0
	v_mov_b32_e32 v50, v0
	v_mov_b32_e32 v51, v0
	v_mov_b32_e32 v52, v0
	v_mov_b32_e32 v53, v0
	v_mov_b32_e32 v54, v0
	v_mov_b32_e32 v55, v0
	v_mov_b32_e32 v56, v0
	v_mov_b32_e32 v57, v0
	v_mov_b32_e32 v58, v0
	v_mov_b32_e32 v59, v0
	v_mov_b32_e32 v60, v0
	v_mov_b32_e32 v61, v0
	v_mov_b32_e32 v62, v0
	v_mov_b32_e32 v63, v0
	v_mov_b32_e32 v64, v0
	v_mov_b32_e32 v65, v0
	v_mov_b32_e32 v66, v0
	v_mov_b32_e32 v67, v0
	v_mov_b32_e32 v68, v0
	v_mov_b32_e32 v69, v0
	v_mov_b32_e32 v70, v0
	v_mov_b32_e32 v71, v0
	v_mov_b32_e32 v72, v0
	v_mov_b32_e32 v73, v0
	v_mov_b32_e32 v74, v0
	v_mov_b32_e32 v75, v0
	v_mov_b32_e32 v76, v0
	v_mov_b32_e32 v77, v0
	v_mov_b32_e32 v78, v0
	v_mov_b32_e32 v79, v0
	v_mov_b32_e32 v80, v0
	v_mov_b32_e32 v81, v0
	v_mov_b32_e32 v82, v0
	v_mov_b32_e32 v83, v0
	v_mov_b32_e32 v84, v0
	v_mov_b32_e32 v85, v0
	v_mov_b32_e32 v86, v0
	v_mov_b32_e32 v87, v0
	v_mov_b32_e32 v88, v0
	v_mov_b32_e32 v89, v0
	v_mov_b32_e32 v90, v0
	v_mov_b32_e32 v91, v0
	v_mov_b32_e32 v92, v0
	v_mov_b32_e32 v93, v0
	v_mov_b32_e32 v94, v0
	v_mov_b32_e32 v95, v0
	v_mov_b32_e32 v96, v0
	v_mov_b32_e32 v97, v0
	v_mov_b32_e32 v98, v0
	v_mov_b32_e32 v99, v0
	v_mov_b32_e32 v100, v0
	v_mov_b32_e32 v101, v0
	v_mov_b32_e32 v102, v0
	v_mov_b32_e32 v103, v0
	v_mov_b32_e32 v104, v0
	v_mov_b32_e32 v105, v0
	v_mov_b32_e32 v106, v0
	v_mov_b32_e32 v107, v0
	v_mov_b32_e32 v108, v0
	v_mov_b32_e32 v109, v0
	v_mov_b32_e32 v110, v0
	v_mov_b32_e32 v111, v0
	v_mov_b32_e32 v112, v0
	v_mov_b32_e32 v113, v0
	v_mov_b32_e32 v114, v0
	v_mov_b32_e32 v115, v0
	v_mov_b32_e32 v116, v0
	v_mov_b32_e32 v117, v0
	v_mov_b32_e32 v118, v0
	v_mov_b32_e32 v119, v0
	v_mov_b32_e32 v120, v0
	v_mov_b32_e32 v121, v0
	v_mov_b32_e32 v122, v0
	v_mov_b32_e32 v123, v0
	v_mov_b32_e32 v124, v0
	v_mov_b32_e32 v125, v0
	v_mov_b32_e32 v126, v0
	v_mov_b32_e32 v127, v0
	s_waitcnt vmcnt(6)
	s_waitcnt lgkmcnt(0)
	v_readlane_b32 s44, v251, 5
	s_nop 0
	s_bitcmp1_b32 s44, 5
	s_cbranch_scc0 .Lnoprio_2
	s_setprio 2

.LBB0_416:
	s_and_b32 s0, s0, 15
	s_or_b32 s18, s0, s50
	v_readlane_b32 s72, v250, 53
	s_lshl_b32 s0, s18, 18
	v_readlane_b32 s78, v250, 59
	v_readlane_b32 s79, v250, 60
	s_add_u32 s4, s78, s0
	v_mov_b32_e32 v3, v200
	v_readlane_b32 s80, v250, 61
	s_addc_u32 s5, s79, 0
	s_lshl_b32 s0, s17, 18
	v_ashrrev_i32_e32 v36, 3, v3
	v_lshlrev_b32_e32 v0, 3, v3
	v_readlane_b32 s81, v250, 62
	s_nop 0
	v_and_b32_e32 v148, 56, v0
	s_add_u32 s6, s80, s0
	v_add_u32_e32 v40, 32, v36
	v_add_u32_e32 v44, 64, v36
	v_add_u32_e32 v48, 0x60, v36
	v_lshlrev_b32_e32 v196, 1, v148
	v_ashrrev_i32_e32 v37, 31, v36
	v_ashrrev_i32_e32 v41, 31, v40
	s_addc_u32 s7, s81, 0
	v_ashrrev_i32_e32 v45, 31, v44
	v_ashrrev_i32_e32 v49, 31, v48
	v_lshl_add_u64 v[128:129], s[4:5], 0, v[196:197]
	v_lshlrev_b64 v[130:131], 11, v[36:37]
	v_lshlrev_b64 v[132:133], 11, v[40:41]
	v_lshlrev_b64 v[134:135], 11, v[44:45]
	v_lshlrev_b64 v[136:137], 11, v[48:49]
	v_lshl_add_u64 v[138:139], s[6:7], 0, v[196:197]
	v_lshl_add_u64 v[38:39], v[128:129], 0, v[130:131]
	v_lshl_add_u64 v[42:43], v[128:129], 0, v[132:133]
	v_lshl_add_u64 v[46:47], v[128:129], 0, v[134:135]
	v_lshl_add_u64 v[50:51], v[128:129], 0, v[136:137]
	v_lshl_add_u64 v[52:53], v[138:139], 0, v[130:131]
	v_lshl_add_u64 v[54:55], v[138:139], 0, v[132:133]
	v_and_b32_e32 v184, 63, v200
	v_readfirstlane_b32 s2, v200
	v_lshrrev_b32_e32 v185, 3, v184
	v_and_b32_e32 v186, 7, v184
	v_lshrrev_b32_e32 v187, 4, v184
	s_lshr_b32 s2, s2, 6
	v_xor_b32_e32 v186, v186, v187
	v_lshlrev_b32_e32 v186, 4, v186
	v_xor_b32_e32 v187, 64, v186
	s_lshl_b32 s32, s2, 5
	v_add_u32_e32 v185, s32, v185
	v_lshlrev_b32_e32 v188, 11, v185
	v_add_u32_e32 v166, v188, v186
	v_add_u32_e32 v167, v188, v187
	v_add_u32_e32 v168, 0x8000, v166
	v_add_u32_e32 v169, 0x8000, v167
	v_add_u32_e32 v167, 0x4000, v167
	v_add_u32_e32 v169, 0x4000, v169
	v_and_b32_e32 v185, 15, v184
	v_lshrrev_b32_e32 v186, 4, v184
	v_bfe_u32 v187, v184, 1, 3
	v_xor_b32_e32 v186, v186, v187
	v_lshlrev_b32_e32 v186, 4, v186
	v_lshl_add_u32 v186, v185, 7, v186
	s_lshr_b32 s32, s2, 1
	s_lshl_b32 s32, s32, 13
	v_add_u32_e32 v170, s32, v186
	s_and_b32 s32, s2, 1
	s_lshl_b32 s32, s32, 13
	s_add_u32 s32, s32, 0x4000
	v_add_u32_e32 v174, s32, v186
	v_xor_b32_e32 v171, 64, v170
	v_xor_b32_e32 v175, 64, v174
	v_xor_b32_e32 v172, 64, v170
	v_xor_b32_e32 v176, 64, v174
	v_xor_b32_e32 v173, 96, v170
	v_xor_b32_e32 v177, 96, v174
	s_lshl_b32 s32, s2, 12
	s_add_u32 s49, s32, 0x4000
	s_mov_b32 s8, s4
	s_mov_b32 s9, s5
	s_mov_b32 s46, s6
	s_mov_b32 s47, s7
	s_add_u32 m0, s32, 0x0
	s_nop 0
	global_load_lds_dwordx4 v166, s[8:9]
	s_add_u32 m0, m0, 0x400
	s_nop 0
	global_load_lds_dwordx4 v167, s[8:9]
	s_add_u32 m0, m0, 0x400
	s_nop 0
	global_load_lds_dwordx4 v168, s[8:9]
	s_add_u32 m0, m0, 0x400
	s_nop 0
	global_load_lds_dwordx4 v169, s[8:9]
	s_add_u32 m0, s32, 0x4000
	s_nop 0
	global_load_lds_dwordx4 v166, s[46:47]
	s_add_u32 m0, m0, 0x400
	s_nop 0
	global_load_lds_dwordx4 v167, s[46:47]
	s_add_u32 m0, m0, 0x400
	s_nop 0
	global_load_lds_dwordx4 v168, s[46:47]
	s_add_u32 m0, m0, 0x400
	s_nop 0
	global_load_lds_dwordx4 v169, s[46:47]
	s_add_u32 s8, s8, 128
	s_addc_u32 s9, s9, 0
	s_add_u32 s46, s46, 128
	s_addc_u32 s47, s47, 0
	v_lshl_add_u64 v[56:57], v[138:139], 0, v[134:135]
	v_lshl_add_u64 v[58:59], v[138:139], 0, v[136:137]
	v_and_b32_e32 v60, 31, v3
	v_lshrrev_b32_e32 v61, 1, v3
	v_and_b32_e32 v3, 0x5f, v3
	s_movk_i32 s2, 0x90
	v_and_or_b32 v60, v61, s23, v60
	v_and_b32_e32 v61, 16, v61
	v_mad_u32_u24 v3, v3, s2, 0
	v_mul_lo_u32 v62, v36, s2
	v_mul_lo_u32 v60, v60, s2
	v_add_u32_e32 v149, v3, v61
	v_add_u32_e32 v3, 0, v196
	v_mov_b32_e32 v0, 0
	v_add_u32_e32 v63, 0x1200, v62
	v_lshlrev_b64 v[36:37], 10, v[36:37]
	v_lshlrev_b64 v[40:41], 10, v[40:41]
	v_lshlrev_b64 v[44:45], 10, v[44:45]
	v_lshlrev_b64 v[48:49], 10, v[48:49]
	v_add_u32_e32 v60, 0, v60
	v_add_u32_e32 v150, v3, v62
	s_movk_i32 s0, 0x80
	s_mov_b32 s1, 0
	v_mov_b32_e32 v1, v0
	v_mov_b32_e32 v2, v0
	v_lshlrev_b64 v[140:141], 1, v[36:37]
	v_add_u32_e32 v151, v3, v63
	v_lshlrev_b64 v[142:143], 1, v[40:41]
	v_lshlrev_b64 v[144:145], 1, v[44:45]
	v_lshlrev_b64 v[146:147], 1, v[48:49]
	v_add_u32_e32 v152, v60, v61
	v_mov_b32_e32 v3, v0
	v_mov_b32_e32 v36, v0
	v_mov_b32_e32 v37, v0
	v_mov_b32_e32 v38, v0
	v_mov_b32_e32 v39, v0
	v_mov_b32_e32 v40, v0
	v_mov_b32_e32 v41, v0
	v_mov_b32_e32 v42, v0
	v_mov_b32_e32 v43, v0
	v_mov_b32_e32 v44, v0
	v_mov_b32_e32 v45, v0
	v_mov_b32_e32 v46, v0
	v_mov_b32_e32 v47, v0
	v_mov_b32_e32 v4, v0
	v_mov_b32_e32 v5, v0
	v_mov_b32_e32 v6, v0
	v_mov_b32_e32 v7, v0
	v_mov_b32_e32 v8, v0
	v_mov_b32_e32 v9, v0
	v_mov_b32_e32 v10, v0
	v_mov_b32_e32 v11, v0
	v_mov_b32_e32 v12, v0
	v_mov_b32_e32 v13, v0
	v_mov_b32_e32 v14, v0
	v_mov_b32_e32 v15, v0
	v_mov_b32_e32 v16, v0
	v_mov_b32_e32 v17, v0
	v_mov_b32_e32 v18, v0
	v_mov_b32_e32 v19, v0
	v_mov_b32_e32 v20, v0
	v_mov_b32_e32 v21, v0
	v_mov_b32_e32 v22, v0
	v_mov_b32_e32 v23, v0
	v_mov_b32_e32 v24, v0
	v_mov_b32_e32 v25, v0
	v_mov_b32_e32 v26, v0
	v_mov_b32_e32 v27, v0
	v_mov_b32_e32 v28, v0
	v_mov_b32_e32 v29, v0
	v_mov_b32_e32 v30, v0
	v_mov_b32_e32 v31, v0
	v_mov_b32_e32 v32, v0
	v_mov_b32_e32 v33, v0
	v_mov_b32_e32 v34, v0
	v_mov_b32_e32 v35, v0
	v_mov_b32_e32 v48, v0
	v_mov_b32_e32 v49, v0
	v_mov_b32_e32 v50, v0
	v_mov_b32_e32 v51, v0
	v_mov_b32_e32 v52, v0
	v_mov_b32_e32 v53, v0
	v_mov_b32_e32 v54, v0
	v_mov_b32_e32 v55, v0
	v_mov_b32_e32 v56, v0
	v_mov_b32_e32 v57, v0
	v_mov_b32_e32 v58, v0
	v_mov_b32_e32 v59, v0
	v_mov_b32_e32 v60, v0
	v_mov_b32_e32 v61, v0
	v_mov_b32_e32 v62, v0
	v_mov_b32_e32 v63, v0
	v_readlane_b32 s73, v250, 54
	v_readlane_b32 s74, v250, 55
	v_readlane_b32 s75, v250, 56
	v_readlane_b32 s76, v250, 57
	v_readlane_b32 s77, v250, 58
	v_readlane_b32 s82, v250, 63
	v_readlane_b32 s83, v249, 0
	v_readlane_b32 s84, v249, 1
	v_readlane_b32 s85, v249, 2
	v_readlane_b32 s86, v249, 3
	v_readlane_b32 s87, v249, 4
	s_mov_b32 s0, 0x8000
	s_waitcnt vmcnt(0)
	s_waitcnt lgkmcnt(0)
	v_readlane_b32 s2, v251, 5
	s_nop 0
	s_bitcmp1_b32 s2, 5
	s_cbranch_scc0 .Lnoprio_3
	s_setprio 2

.LBB0_448:
	s_ashr_i32 s6, s12, 3
	s_ashr_i32 s7, s6, 31
	s_and_b32 s1, s12, 7
	s_lshl_b64 s[4:5], s[6:7], 17
	s_lshl_b64 s[6:7], s[6:7], 18
	s_add_u32 s6, s56, s6
	v_readlane_b32 s16, v250, 53
	v_mov_b32_e32 v1, v200
	s_addc_u32 s7, s57, s7
	s_lshl_b32 s2, s1, 18
	v_readlane_b32 s30, v249, 3
	v_readlane_b32 s31, v249, 4
	v_ashrrev_i32_e32 v34, 3, v1
	v_lshlrev_b32_e32 v0, 3, v1
	s_add_u32 s8, s30, s2
	s_nop 0
	v_and_b32_e32 v148, 56, v0
	v_add_u32_e32 v40, 32, v34
	v_add_u32_e32 v46, 64, v34
	v_add_u32_e32 v50, 0x60, v34
	s_addc_u32 s9, s31, 0
	v_lshlrev_b32_e32 v196, 1, v148
	v_ashrrev_i32_e32 v35, 31, v34
	v_ashrrev_i32_e32 v41, 31, v40
	v_ashrrev_i32_e32 v47, 31, v46
	v_ashrrev_i32_e32 v51, 31, v50
	v_lshl_add_u64 v[128:129], s[6:7], 0, v[196:197]
	v_lshl_add_u64 v[130:131], s[8:9], 0, v[196:197]
	v_lshlrev_b64 v[132:133], 11, v[34:35]
	v_lshlrev_b64 v[134:135], 11, v[40:41]
	v_lshlrev_b64 v[136:137], 11, v[46:47]
	v_lshlrev_b64 v[138:139], 11, v[50:51]
	v_lshl_add_u64 v[36:37], v[128:129], 0, v[132:133]
	v_lshl_add_u64 v[38:39], v[130:131], 0, v[132:133]
	v_lshl_add_u64 v[42:43], v[128:129], 0, v[134:135]
	v_lshl_add_u64 v[44:45], v[130:131], 0, v[134:135]
	v_lshl_add_u64 v[48:49], v[128:129], 0, v[136:137]
	v_lshl_add_u64 v[52:53], v[128:129], 0, v[138:139]
	v_lshl_add_u64 v[54:55], v[130:131], 0, v[136:137]
	v_lshl_add_u64 v[56:57], v[130:131], 0, v[138:139]
	v_and_b32_e32 v184, 63, v200
	v_readfirstlane_b32 s2, v200
	v_lshrrev_b32_e32 v185, 3, v184
	v_and_b32_e32 v186, 7, v184
	v_lshrrev_b32_e32 v187, 4, v184
	s_lshr_b32 s2, s2, 6
	v_xor_b32_e32 v186, v186, v187
	v_lshlrev_b32_e32 v186, 4, v186
	v_xor_b32_e32 v187, 64, v186
	s_lshl_b32 s32, s2, 5
	v_add_u32_e32 v185, s32, v185
	v_lshlrev_b32_e32 v188, 11, v185
	v_add_u32_e32 v166, v188, v186
	v_add_u32_e32 v167, v188, v187
	v_add_u32_e32 v168, 0x8000, v166
	v_add_u32_e32 v169, 0x8000, v167
	v_add_u32_e32 v167, 0x4000, v167
	v_add_u32_e32 v169, 0x4000, v169
	v_and_b32_e32 v185, 15, v184
	v_lshrrev_b32_e32 v186, 4, v184
	v_bfe_u32 v187, v184, 1, 3
	v_xor_b32_e32 v186, v186, v187
	v_lshlrev_b32_e32 v186, 4, v186
	v_lshl_add_u32 v186, v185, 7, v186
	s_lshr_b32 s32, s2, 1
	s_lshl_b32 s32, s32, 13
	v_add_u32_e32 v170, s32, v186
	s_and_b32 s32, s2, 1
	s_lshl_b32 s32, s32, 13
	s_add_u32 s32, s32, 0x4000
	v_add_u32_e32 v174, s32, v186
	v_xor_b32_e32 v171, 64, v170
	v_xor_b32_e32 v175, 64, v174
	v_xor_b32_e32 v172, 64, v170
	v_xor_b32_e32 v176, 64, v174
	v_xor_b32_e32 v173, 96, v170
	v_xor_b32_e32 v177, 96, v174
	s_lshl_b32 s32, s2, 12
	s_add_u32 s49, s32, 0x4000
	s_mov_b32 s10, s6
	s_mov_b32 s11, s7
	s_mov_b32 s46, s8
	s_mov_b32 s47, s9
	s_add_u32 m0, s32, 0x0
	s_nop 0
	global_load_lds_dwordx4 v166, s[10:11]
	s_add_u32 m0, m0, 0x400
	s_nop 0
	global_load_lds_dwordx4 v167, s[10:11]
	s_add_u32 m0, m0, 0x400
	s_nop 0
	global_load_lds_dwordx4 v168, s[10:11]
	s_add_u32 m0, m0, 0x400
	s_nop 0
	global_load_lds_dwordx4 v169, s[10:11]
	s_add_u32 m0, s32, 0x4000
	s_nop 0
	global_load_lds_dwordx4 v166, s[46:47]
	s_add_u32 m0, m0, 0x400
	s_nop 0
	global_load_lds_dwordx4 v167, s[46:47]
	s_add_u32 m0, m0, 0x400
	s_nop 0
	global_load_lds_dwordx4 v168, s[46:47]
	s_add_u32 m0, m0, 0x400
	s_nop 0
	global_load_lds_dwordx4 v169, s[46:47]
	s_add_u32 s10, s10, 128
	s_addc_u32 s11, s11, 0
	s_add_u32 s46, s46, 128
	s_addc_u32 s47, s47, 0
	v_and_b32_e32 v58, 31, v1
	v_lshrrev_b32_e32 v59, 1, v1
	v_and_b32_e32 v1, 0x5f, v1
	s_movk_i32 s2, 0x90
	v_and_or_b32 v58, v59, s10, v58
	v_and_b32_e32 v59, 16, v59
	v_mad_u32_u24 v1, v1, s2, 0
	v_mul_lo_u32 v60, v34, s2
	v_mul_lo_u32 v58, v58, s2
	v_add_u32_e32 v149, v1, v59
	v_add_u32_e32 v1, 0, v196
	v_mov_b32_e32 v0, 0
	v_lshlrev_b64 v[34:35], 10, v[34:35]
	v_add_u32_e32 v61, 0x1200, v60
	v_lshlrev_b64 v[40:41], 10, v[40:41]
	v_lshlrev_b64 v[46:47], 10, v[46:47]
	v_lshlrev_b64 v[50:51], 10, v[50:51]
	v_add_u32_e32 v58, 0, v58
	v_add_u32_e32 v150, v1, v60
	s_mov_b32 s13, 0
	s_movk_i32 s14, 0x80
	v_lshlrev_b64 v[140:141], 1, v[34:35]
	v_add_u32_e32 v151, v1, v61
	v_lshlrev_b64 v[142:143], 1, v[40:41]
	v_lshlrev_b64 v[144:145], 1, v[46:47]
	v_lshlrev_b64 v[146:147], 1, v[50:51]
	v_add_u32_e32 v152, v58, v59
	v_mov_b32_e32 v1, v0
	v_mov_b32_e32 v34, v0
	v_mov_b32_e32 v35, v0
	v_mov_b32_e32 v36, v0
	v_mov_b32_e32 v37, v0
	v_mov_b32_e32 v38, v0
	v_mov_b32_e32 v39, v0
	v_mov_b32_e32 v40, v0
	v_mov_b32_e32 v41, v0
	v_mov_b32_e32 v42, v0
	v_mov_b32_e32 v43, v0
	v_mov_b32_e32 v2, v0
	v_mov_b32_e32 v3, v0
	v_mov_b32_e32 v4, v0
	v_mov_b32_e32 v5, v0
	v_mov_b32_e32 v6, v0
	v_mov_b32_e32 v7, v0
	v_mov_b32_e32 v8, v0
	v_mov_b32_e32 v9, v0
	v_mov_b32_e32 v10, v0
	v_mov_b32_e32 v11, v0
	v_mov_b32_e32 v12, v0
	v_mov_b32_e32 v13, v0
	v_mov_b32_e32 v14, v0
	v_mov_b32_e32 v15, v0
	v_mov_b32_e32 v16, v0
	v_mov_b32_e32 v17, v0
	v_mov_b32_e32 v18, v0
	v_mov_b32_e32 v19, v0
	v_mov_b32_e32 v20, v0
	v_mov_b32_e32 v21, v0
	v_mov_b32_e32 v22, v0
	v_mov_b32_e32 v23, v0
	v_mov_b32_e32 v24, v0
	v_mov_b32_e32 v25, v0
	v_mov_b32_e32 v26, v0
	v_mov_b32_e32 v27, v0
	v_mov_b32_e32 v28, v0
	v_mov_b32_e32 v29, v0
	v_mov_b32_e32 v30, v0
	v_mov_b32_e32 v31, v0
	v_mov_b32_e32 v32, v0
	v_mov_b32_e32 v33, v0
	v_mov_b32_e32 v44, v0
	v_mov_b32_e32 v45, v0
	v_mov_b32_e32 v46, v0
	v_mov_b32_e32 v47, v0
	v_mov_b32_e32 v48, v0
	v_mov_b32_e32 v49, v0
	v_mov_b32_e32 v50, v0
	v_mov_b32_e32 v51, v0
	v_mov_b32_e32 v52, v0
	v_mov_b32_e32 v53, v0
	v_mov_b32_e32 v54, v0
	v_mov_b32_e32 v55, v0
	v_mov_b32_e32 v56, v0
	v_mov_b32_e32 v57, v0
	v_mov_b32_e32 v58, v0
	v_mov_b32_e32 v59, v0
	v_mov_b32_e32 v60, v0
	v_mov_b32_e32 v61, v0
	v_mov_b32_e32 v62, v0
	v_mov_b32_e32 v63, v0
	s_mov_b32 s15, 0xfffffc0
	v_readlane_b32 s17, v250, 54
	v_readlane_b32 s18, v250, 55
	v_readlane_b32 s19, v250, 56
	v_readlane_b32 s20, v250, 57
	v_readlane_b32 s21, v250, 58
	v_readlane_b32 s22, v250, 59
	v_readlane_b32 s23, v250, 60
	v_readlane_b32 s24, v250, 61
	v_readlane_b32 s25, v250, 62
	v_readlane_b32 s26, v250, 63
	v_readlane_b32 s27, v249, 0
	v_readlane_b32 s28, v249, 1
	v_readlane_b32 s29, v249, 2
	s_mov_b32 s14, 0x8000
	s_waitcnt vmcnt(0)
	s_waitcnt lgkmcnt(0)
	v_readlane_b32 s2, v251, 5
	s_nop 0
	s_bitcmp1_b32 s2, 5
	s_cbranch_scc0 .Lnoprio_4
	s_setprio 2
